# v077 + accumulator clears removed: first K-loop iteration of the in-projection and FFN-in units peeled, first MFMA per accumulator takes C = 0; FFN-in unit mapping strength-reduced
# speedup vs baseline: 1.0104x; 1.0104x over previous
.LBB0_232:
	s_ashr_i32 s71, s70, 31
	s_lshl_b64 s[72:73], s[70:71], 19
	s_add_u32 s72, s84, s72
	s_addc_u32 s73, s34, s73
	s_and_b64 s[74:75], s[12:13], exec
	s_cselect_b32 s15, s73, s19
	s_cselect_b32 s17, s72, s18
	s_ashr_i32 s69, s68, 31
	s_lshl_b64 s[74:75], s[68:69], 19
	s_add_u32 s74, s83, s74
	s_addc_u32 s75, s97, s75
	s_and_b64 s[78:79], s[12:13], exec
	s_cselect_b32 s24, s75, s77
	s_cselect_b32 s69, s74, s76
	s_add_u32 s18, s18, 0x40080
	s_addc_u32 s19, s19, 0
	s_add_u32 s71, s76, 0x100
	s_addc_u32 vcc_lo, s77, 0
	s_mov_b32 vcc_hi, -2
	s_waitcnt lgkmcnt(0)
	s_add_u32 s6, s18, 0xfffc0080
	s_addc_u32 s33, s19, -1
	s_add_i32 s94, 0, 0x10000
	s_cmp_eq_u32 vcc_hi, 12
	s_cselect_b32 s79, s15, s33
	s_cselect_b32 s78, s17, s6
	s_cselect_b32 s77, s24, vcc_lo
	s_cselect_b32 s76, s69, s71
	s_add_i32 s6, 0, 0x14000
	v_add_u32_e32 v36, s94, v184
	v_add_u32_e32 v168, s6, v184
	ds_read_b128 v[20:23], v36
	ds_read_b128 v[24:27], v36 offset:1024
	ds_read_b128 v[28:31], v36 offset:2048
	ds_read_b128 v[36:39], v36 offset:3072
	ds_read_b128 v[158:161], v168
	ds_read_b128 v[162:165], v168 offset:1024
	ds_read_b128 v[174:177], v168 offset:2048
	ds_read_b128 v[178:181], v168 offset:3072
	v_lshl_add_u64 v[168:169], s[18:19], 0, v[154:155]
	s_add_i32 m0, s35, 0xc000
	ds_read_b128 v[208:211], v206
	ds_read_b128 v[212:215], v206 offset:1024
	ds_read_b128 v[216:219], v206 offset:2048
	ds_read_b128 v[220:223], v206 offset:3072
	ds_read_b128 v[224:227], v206 offset:4096
	ds_read_b128 v[228:231], v206 offset:5120
	ds_read_b128 v[232:235], v206 offset:6144
	ds_read_b128 v[236:239], v206 offset:7168
	global_load_lds_dwordx4 v[168:169], off
	v_lshl_add_u64 v[168:169], s[18:19], 0, v[156:157]
	s_add_i32 m0, s35, 0xe000
	s_nop 0
	global_load_lds_dwordx4 v[168:169], off
	s_waitcnt vmcnt(8)
	s_waitcnt lgkmcnt(0)
	s_barrier
	s_waitcnt lgkmcnt(0)
	v_mfma_f32_16x16x32_bf16 v[144:147], v[20:23], v[208:211], 0
	v_mfma_f32_16x16x32_bf16 v[140:143], v[28:31], v[208:211], 0
	v_mfma_f32_16x16x32_bf16 v[128:131], v[20:23], v[216:219], 0
	v_mfma_f32_16x16x32_bf16 v[124:127], v[28:31], v[216:219], 0
	v_mfma_f32_16x16x32_bf16 v[112:115], v[20:23], v[224:227], 0
	v_mfma_f32_16x16x32_bf16 v[108:111], v[28:31], v[224:227], 0
	v_mfma_f32_16x16x32_bf16 v[96:99], v[20:23], v[232:235], 0
	v_mfma_f32_16x16x32_bf16 v[92:95], v[28:31], v[232:235], 0
	v_mfma_f32_16x16x32_bf16 v[144:147], v[24:27], v[212:215], v[144:147]
	v_mfma_f32_16x16x32_bf16 v[140:143], v[36:39], v[212:215], v[140:143]
	v_mfma_f32_16x16x32_bf16 v[128:131], v[24:27], v[220:223], v[128:131]
	v_mfma_f32_16x16x32_bf16 v[124:127], v[36:39], v[220:223], v[124:127]
	v_mfma_f32_16x16x32_bf16 v[112:115], v[24:27], v[228:231], v[112:115]
	v_mfma_f32_16x16x32_bf16 v[108:111], v[36:39], v[228:231], v[108:111]
	v_mfma_f32_16x16x32_bf16 v[96:99], v[24:27], v[236:239], v[96:99]
	v_mfma_f32_16x16x32_bf16 v[92:95], v[36:39], v[236:239], v[92:95]
	v_mfma_f32_16x16x32_bf16 v[136:139], v[158:161], v[208:211], 0
	v_mfma_f32_16x16x32_bf16 v[132:135], v[174:177], v[208:211], 0
	v_mfma_f32_16x16x32_bf16 v[120:123], v[158:161], v[216:219], 0
	v_mfma_f32_16x16x32_bf16 v[116:119], v[174:177], v[216:219], 0
	v_mfma_f32_16x16x32_bf16 v[104:107], v[158:161], v[224:227], 0
	v_mfma_f32_16x16x32_bf16 v[100:103], v[174:177], v[224:227], 0
	v_mfma_f32_16x16x32_bf16 v[88:91], v[158:161], v[232:235], 0
	v_mfma_f32_16x16x32_bf16 v[84:87], v[174:177], v[232:235], 0
	v_mfma_f32_16x16x32_bf16 v[136:139], v[162:165], v[212:215], v[136:139]
	v_mfma_f32_16x16x32_bf16 v[132:135], v[178:181], v[212:215], v[132:135]
	v_mfma_f32_16x16x32_bf16 v[120:123], v[162:165], v[220:223], v[120:123]
	v_mfma_f32_16x16x32_bf16 v[116:119], v[178:181], v[220:223], v[116:119]
	v_mfma_f32_16x16x32_bf16 v[104:107], v[162:165], v[228:231], v[104:107]
	v_mfma_f32_16x16x32_bf16 v[100:103], v[178:181], v[228:231], v[100:103]
	v_mfma_f32_16x16x32_bf16 v[88:91], v[162:165], v[236:239], v[88:91]
	v_mfma_f32_16x16x32_bf16 v[84:87], v[178:181], v[236:239], v[84:87]
	s_barrier
	s_add_i32 s33, s94, s57
	v_lshl_add_u64 v[168:169], s[76:77], 0, v[2:3]
	s_mov_b32 m0, s33
	ds_read_b128 v[208:211], v206 offset:16384
	ds_read_b128 v[212:215], v206 offset:17408
	ds_read_b128 v[216:219], v206 offset:18432
	ds_read_b128 v[220:223], v206 offset:19456
	ds_read_b128 v[224:227], v206 offset:20480
	ds_read_b128 v[228:231], v206 offset:21504
	ds_read_b128 v[232:235], v206 offset:22528
	ds_read_b128 v[236:239], v206 offset:23552
	global_load_lds_dwordx4 v[168:169], off
	s_add_i32 m0, s33, 0x2000
	s_add_u32 s94, s76, 0x40000
	v_lshl_add_u64 v[170:171], s[76:77], 0, v[152:153]
	s_addc_u32 s95, s77, 0
	s_add_i32 s6, s6, s57
	global_load_lds_dwordx4 v[170:171], off
	v_lshl_add_u64 v[182:183], s[94:95], 0, v[2:3]
	s_mov_b32 m0, s6
	v_lshl_add_u64 v[240:241], s[78:79], 0, v[150:151]
	global_load_lds_dwordx4 v[182:183], off
	v_lshl_add_u64 v[182:183], s[94:95], 0, v[152:153]
	s_add_i32 m0, s6, 0x2000
	s_nop 0
	global_load_lds_dwordx4 v[182:183], off
	v_lshl_add_u64 v[182:183], s[78:79], 0, v[148:149]
	s_mov_b32 m0, s35
	s_nop 0
	global_load_lds_dwordx4 v[182:183], off
	s_mov_b32 m0, s9
	s_nop 0
	global_load_lds_dwordx4 v[240:241], off
	s_waitcnt vmcnt(8)
	s_waitcnt lgkmcnt(0)
	s_barrier
	s_waitcnt lgkmcnt(0)
	v_mfma_f32_16x16x32_bf16 v[80:83], v[20:23], v[208:211], 0
	v_mfma_f32_16x16x32_bf16 v[76:79], v[28:31], v[208:211], 0
	v_mfma_f32_16x16x32_bf16 v[64:67], v[20:23], v[216:219], 0
	v_mfma_f32_16x16x32_bf16 v[60:63], v[28:31], v[216:219], 0
	v_mfma_f32_16x16x32_bf16 v[48:51], v[20:23], v[224:227], 0
	v_mfma_f32_16x16x32_bf16 v[44:47], v[28:31], v[224:227], 0
	v_mfma_f32_16x16x32_bf16 v[16:19], v[20:23], v[232:235], 0
	v_mfma_f32_16x16x32_bf16 v[12:15], v[28:31], v[232:235], 0
	v_mfma_f32_16x16x32_bf16 v[80:83], v[24:27], v[212:215], v[80:83]
	v_mfma_f32_16x16x32_bf16 v[76:79], v[36:39], v[212:215], v[76:79]
	v_mfma_f32_16x16x32_bf16 v[64:67], v[24:27], v[220:223], v[64:67]
	v_mfma_f32_16x16x32_bf16 v[60:63], v[36:39], v[220:223], v[60:63]
	v_mfma_f32_16x16x32_bf16 v[48:51], v[24:27], v[228:231], v[48:51]
	v_mfma_f32_16x16x32_bf16 v[44:47], v[36:39], v[228:231], v[44:47]
	v_mfma_f32_16x16x32_bf16 v[16:19], v[24:27], v[236:239], v[16:19]
	v_mfma_f32_16x16x32_bf16 v[12:15], v[36:39], v[236:239], v[12:15]
	v_mfma_f32_16x16x32_bf16 v[40:43], v[158:161], v[224:227], 0
	v_mfma_f32_16x16x32_bf16 v[32:35], v[174:177], v[224:227], 0
	v_mfma_f32_16x16x32_bf16 v[8:11], v[158:161], v[232:235], 0
	v_mfma_f32_16x16x32_bf16 v[4:7], v[174:177], v[232:235], 0
	v_mfma_f32_16x16x32_bf16 v[20:23], v[158:161], v[208:211], 0
	v_mfma_f32_16x16x32_bf16 v[24:27], v[174:177], v[208:211], 0
	v_mfma_f32_16x16x32_bf16 v[28:31], v[158:161], v[216:219], 0
	v_mfma_f32_16x16x32_bf16 v[36:39], v[174:177], v[216:219], 0
	v_mfma_f32_16x16x32_bf16 v[40:43], v[162:165], v[228:231], v[40:43]
	v_mfma_f32_16x16x32_bf16 v[32:35], v[178:181], v[228:231], v[32:35]
	v_mfma_f32_16x16x32_bf16 v[8:11], v[162:165], v[236:239], v[8:11]
	v_mfma_f32_16x16x32_bf16 v[4:7], v[178:181], v[236:239], v[4:7]
	v_mfma_f32_16x16x32_bf16 v[20:23], v[162:165], v[212:215], v[20:23]
	v_mfma_f32_16x16x32_bf16 v[24:27], v[178:181], v[212:215], v[24:27]
	v_mfma_f32_16x16x32_bf16 v[28:31], v[162:165], v[220:223], v[28:31]
	v_mfma_f32_16x16x32_bf16 v[36:39], v[178:181], v[220:223], v[36:39]
	s_barrier
	s_add_i32 s6, 0, 0x18000
	s_add_i32 s33, 0, 0x1c000
	v_add_u32_e32 v72, s6, v184
	v_add_u32_e32 v178, s33, v184
	ds_read_b128 v[52:55], v72
	ds_read_b128 v[56:59], v72 offset:1024
	ds_read_b128 v[68:71], v72 offset:2048
	ds_read_b128 v[72:75], v72 offset:3072
	ds_read_b128 v[158:161], v178
	ds_read_b128 v[162:165], v178 offset:1024
	ds_read_b128 v[174:177], v178 offset:2048
	ds_read_b128 v[178:181], v178 offset:3072
	s_add_u32 s78, s78, 0x40000
	s_addc_u32 s79, s79, 0
	s_mov_b32 m0, s4
	v_lshl_add_u64 v[242:243], s[78:79], 0, v[148:149]
	ds_read_b128 v[208:211], v206 offset:32768
	ds_read_b128 v[212:215], v206 offset:33792
	ds_read_b128 v[216:219], v206 offset:34816
	ds_read_b128 v[220:223], v206 offset:35840
	ds_read_b128 v[224:227], v206 offset:36864
	ds_read_b128 v[228:231], v206 offset:37888
	ds_read_b128 v[232:235], v206 offset:38912
	ds_read_b128 v[236:239], v206 offset:39936
	global_load_lds_dwordx4 v[242:243], off
	v_lshl_add_u64 v[242:243], s[78:79], 0, v[150:151]
	s_mov_b32 m0, s20
	s_nop 0
	global_load_lds_dwordx4 v[242:243], off
	s_waitcnt vmcnt(8)
	s_waitcnt lgkmcnt(0)
	s_barrier
	s_waitcnt lgkmcnt(0)
	v_mfma_f32_16x16x32_bf16 v[144:147], v[52:55], v[208:211], v[144:147]
	v_mfma_f32_16x16x32_bf16 v[140:143], v[68:71], v[208:211], v[140:143]
	v_mfma_f32_16x16x32_bf16 v[128:131], v[52:55], v[216:219], v[128:131]
	v_mfma_f32_16x16x32_bf16 v[124:127], v[68:71], v[216:219], v[124:127]
	v_mfma_f32_16x16x32_bf16 v[112:115], v[52:55], v[224:227], v[112:115]
	v_mfma_f32_16x16x32_bf16 v[108:111], v[68:71], v[224:227], v[108:111]
	v_mfma_f32_16x16x32_bf16 v[96:99], v[52:55], v[232:235], v[96:99]
	v_mfma_f32_16x16x32_bf16 v[92:95], v[68:71], v[232:235], v[92:95]
	v_mfma_f32_16x16x32_bf16 v[144:147], v[56:59], v[212:215], v[144:147]
	v_mfma_f32_16x16x32_bf16 v[140:143], v[72:75], v[212:215], v[140:143]
	v_mfma_f32_16x16x32_bf16 v[128:131], v[56:59], v[220:223], v[128:131]
	v_mfma_f32_16x16x32_bf16 v[124:127], v[72:75], v[220:223], v[124:127]
	v_mfma_f32_16x16x32_bf16 v[112:115], v[56:59], v[228:231], v[112:115]
	v_mfma_f32_16x16x32_bf16 v[108:111], v[72:75], v[228:231], v[108:111]
	v_mfma_f32_16x16x32_bf16 v[96:99], v[56:59], v[236:239], v[96:99]
	v_mfma_f32_16x16x32_bf16 v[92:95], v[72:75], v[236:239], v[92:95]
	v_mfma_f32_16x16x32_bf16 v[136:139], v[158:161], v[208:211], v[136:139]
	v_mfma_f32_16x16x32_bf16 v[132:135], v[174:177], v[208:211], v[132:135]
	v_mfma_f32_16x16x32_bf16 v[120:123], v[158:161], v[216:219], v[120:123]
	v_mfma_f32_16x16x32_bf16 v[116:119], v[174:177], v[216:219], v[116:119]
	v_mfma_f32_16x16x32_bf16 v[104:107], v[158:161], v[224:227], v[104:107]
	v_mfma_f32_16x16x32_bf16 v[100:103], v[174:177], v[224:227], v[100:103]
	v_mfma_f32_16x16x32_bf16 v[88:91], v[158:161], v[232:235], v[88:91]
	v_mfma_f32_16x16x32_bf16 v[84:87], v[174:177], v[232:235], v[84:87]
	v_mfma_f32_16x16x32_bf16 v[136:139], v[162:165], v[212:215], v[136:139]
	v_mfma_f32_16x16x32_bf16 v[132:135], v[178:181], v[212:215], v[132:135]
	v_mfma_f32_16x16x32_bf16 v[120:123], v[162:165], v[220:223], v[120:123]
	v_mfma_f32_16x16x32_bf16 v[116:119], v[178:181], v[220:223], v[116:119]
	v_mfma_f32_16x16x32_bf16 v[104:107], v[162:165], v[228:231], v[104:107]
	v_mfma_f32_16x16x32_bf16 v[100:103], v[178:181], v[228:231], v[100:103]
	v_mfma_f32_16x16x32_bf16 v[88:91], v[162:165], v[236:239], v[88:91]
	v_mfma_f32_16x16x32_bf16 v[84:87], v[178:181], v[236:239], v[84:87]
	s_barrier
	s_add_i32 s6, s6, s57
	v_lshl_add_u64 v[168:169], v[168:169], 0, s[30:31]
	s_mov_b32 m0, s6
	ds_read_b128 v[208:211], v206 offset:49152
	ds_read_b128 v[212:215], v206 offset:50176
	ds_read_b128 v[216:219], v206 offset:51200
	ds_read_b128 v[220:223], v206 offset:52224
	ds_read_b128 v[224:227], v206 offset:53248
	ds_read_b128 v[228:231], v206 offset:54272
	ds_read_b128 v[232:235], v206 offset:55296
	ds_read_b128 v[236:239], v206 offset:56320
	global_load_lds_dwordx4 v[168:169], off
	s_add_i32 m0, s6, 0x2000
	s_add_u32 s76, s76, 0x40080
	v_lshl_add_u64 v[168:169], v[170:171], 0, s[30:31]
	s_addc_u32 s77, s77, 0
	s_add_i32 s6, s33, s57
	global_load_lds_dwordx4 v[168:169], off
	v_lshl_add_u64 v[168:169], s[76:77], 0, v[2:3]
	s_mov_b32 m0, s6
	s_nop 0
	global_load_lds_dwordx4 v[168:169], off
	v_lshl_add_u64 v[168:169], s[76:77], 0, v[152:153]
	s_add_i32 m0, s6, 0x2000
	s_nop 0
	global_load_lds_dwordx4 v[168:169], off
	v_lshl_add_u64 v[168:169], v[182:183], 0, s[30:31]
	s_mov_b32 m0, s82
	s_nop 0
	global_load_lds_dwordx4 v[168:169], off
	v_lshl_add_u64 v[168:169], v[240:241], 0, s[30:31]
	s_mov_b32 m0, s27
	s_nop 0
	global_load_lds_dwordx4 v[168:169], off
	s_waitcnt vmcnt(8)
	s_waitcnt lgkmcnt(0)
	s_barrier
	s_waitcnt lgkmcnt(0)
	v_mfma_f32_16x16x32_bf16 v[80:83], v[52:55], v[208:211], v[80:83]
	v_mfma_f32_16x16x32_bf16 v[76:79], v[68:71], v[208:211], v[76:79]
	v_mfma_f32_16x16x32_bf16 v[64:67], v[52:55], v[216:219], v[64:67]
	v_mfma_f32_16x16x32_bf16 v[60:63], v[68:71], v[216:219], v[60:63]
	v_mfma_f32_16x16x32_bf16 v[48:51], v[52:55], v[224:227], v[48:51]
	v_mfma_f32_16x16x32_bf16 v[44:47], v[68:71], v[224:227], v[44:47]
	v_mfma_f32_16x16x32_bf16 v[16:19], v[52:55], v[232:235], v[16:19]
	v_mfma_f32_16x16x32_bf16 v[12:15], v[68:71], v[232:235], v[12:15]
	v_mfma_f32_16x16x32_bf16 v[80:83], v[56:59], v[212:215], v[80:83]
	v_mfma_f32_16x16x32_bf16 v[76:79], v[72:75], v[212:215], v[76:79]
	v_mfma_f32_16x16x32_bf16 v[64:67], v[56:59], v[220:223], v[64:67]
	v_mfma_f32_16x16x32_bf16 v[60:63], v[72:75], v[220:223], v[60:63]
	v_mfma_f32_16x16x32_bf16 v[48:51], v[56:59], v[228:231], v[48:51]
	v_mfma_f32_16x16x32_bf16 v[44:47], v[72:75], v[228:231], v[44:47]
	v_mfma_f32_16x16x32_bf16 v[16:19], v[56:59], v[236:239], v[16:19]
	v_mfma_f32_16x16x32_bf16 v[12:15], v[72:75], v[236:239], v[12:15]
	v_mfma_f32_16x16x32_bf16 v[20:23], v[158:161], v[208:211], v[20:23]
	v_mfma_f32_16x16x32_bf16 v[72:75], v[162:165], v[212:215], v[20:23]
	v_mfma_f32_16x16x32_bf16 v[20:23], v[174:177], v[208:211], v[24:27]
	v_mfma_f32_16x16x32_bf16 v[68:71], v[178:181], v[212:215], v[20:23]
	v_mfma_f32_16x16x32_bf16 v[20:23], v[158:161], v[216:219], v[28:31]
	v_mfma_f32_16x16x32_bf16 v[56:59], v[162:165], v[220:223], v[20:23]
	v_mfma_f32_16x16x32_bf16 v[20:23], v[174:177], v[216:219], v[36:39]
	v_mfma_f32_16x16x32_bf16 v[52:55], v[178:181], v[220:223], v[20:23]
	v_mfma_f32_16x16x32_bf16 v[20:23], v[158:161], v[224:227], v[40:43]
	v_mfma_f32_16x16x32_bf16 v[40:43], v[162:165], v[228:231], v[20:23]
	v_mfma_f32_16x16x32_bf16 v[20:23], v[174:177], v[224:227], v[32:35]
	v_mfma_f32_16x16x32_bf16 v[8:11], v[158:161], v[232:235], v[8:11]
	v_mfma_f32_16x16x32_bf16 v[4:7], v[174:177], v[232:235], v[4:7]
	v_mfma_f32_16x16x32_bf16 v[32:35], v[178:181], v[228:231], v[20:23]
	v_mfma_f32_16x16x32_bf16 v[8:11], v[162:165], v[236:239], v[8:11]
	v_mfma_f32_16x16x32_bf16 v[4:7], v[178:181], v[236:239], v[4:7]
	s_barrier
	s_add_i32 vcc_hi, vcc_hi, 2
	s_add_u32 s18, s18, 0x100
	s_addc_u32 s19, s19, 0
	s_add_u32 s71, s71, 0x100
	s_addc_u32 vcc_lo, vcc_lo, 0

.LBB0_661:
	s_add_i32 s79, s79, 1
	s_mul_i32 s6, s79, s78
	s_mul_hi_u32 s10, s79, s4
	s_add_i32 s10, s10, s6
	s_mul_i32 s6, s79, s4
	s_add_u32 s62, s6, s5
	s_addc_u32 s63, s10, s8
	v_mov_b64_e32 v[4:5], 0x580
	v_cmp_lt_i64_e64 s[12:13], s[62:63], v[4:5]
	v_mov_b64_e32 v[4:5], 0x57f
	v_cmp_gt_i64_e32 vcc, s[62:63], v[4:5]
	s_cbranch_vccnz .LBB0_663
	s_mov_b32 s60, s66
	s_add_i32 s58, s14, 4
.LBB0_663:
	s_ashr_i32 s61, s60, 31
	s_lshl_b64 s[10:11], s[60:61], 19
	s_add_u32 s62, s21, s10
	s_addc_u32 s63, s24, s11
	s_and_b64 s[10:11], s[12:13], exec
	s_cselect_b32 s10, s63, s69
	s_cselect_b32 s11, s62, s68
	s_ashr_i32 s59, s58, 31
	s_lshl_b64 s[64:65], s[58:59], 19
	s_add_u32 s64, s27, s64
	s_addc_u32 s65, s34, s65
	s_and_b64 s[72:73], s[12:13], exec
	s_cselect_b32 s15, s65, s71
	s_cselect_b32 s59, s64, s70
	s_add_u32 s68, s68, 0x40080
	s_addc_u32 s69, s69, 0
	s_add_u32 s61, s70, 0x100
	s_addc_u32 s67, s71, 0
	s_mov_b32 s80, -2
	s_add_u32 s6, s68, 0xfffc0080
	s_addc_u32 s33, s69, -1
	s_add_i32 s82, 0, 0x10000
	s_cmp_eq_u32 s80, 12
	s_cselect_b32 s73, s10, s33
	s_cselect_b32 s72, s11, s6
	v_add_u32_e32 v2, s82, v148
	s_cselect_b32 s71, s15, s67
	s_cselect_b32 s70, s59, s61
	s_add_i32 s6, 0, 0x14000
	ds_read_b128 v[152:155], v2
	ds_read_b128 v[156:159], v2 offset:1024
	ds_read_b128 v[160:163], v2 offset:2048
	ds_read_b128 v[168:171], v2 offset:3072
	v_add_u32_e32 v2, s6, v148
	ds_read_b128 v[174:177], v2
	ds_read_b128 v[178:181], v2 offset:1024
	ds_read_b128 v[182:185], v2 offset:2048
	ds_read_b128 v[186:189], v2 offset:3072
	v_lshl_add_u64 v[146:147], s[68:69], 0, v[142:143]
	s_add_i32 m0, s35, 0xc000
	ds_read_b128 v[200:203], v151
	ds_read_b128 v[204:207], v151 offset:1024
	ds_read_b128 v[208:211], v151 offset:2048
	ds_read_b128 v[212:215], v151 offset:3072
	ds_read_b128 v[216:219], v151 offset:4096
	ds_read_b128 v[220:223], v151 offset:5120
	ds_read_b128 v[224:227], v151 offset:6144
	ds_read_b128 v[228:231], v151 offset:7168
	global_load_lds_dwordx4 v[146:147], off
	v_lshl_add_u64 v[146:147], s[68:69], 0, v[144:145]
	s_add_i32 m0, s35, 0xe000
	s_nop 0
	global_load_lds_dwordx4 v[146:147], off
	s_waitcnt vmcnt(8)
	s_waitcnt lgkmcnt(0)
	s_barrier
	s_waitcnt lgkmcnt(0)
	v_mfma_f32_16x16x32_bf16 v[128:131], v[152:155], v[200:203], 0
	v_mfma_f32_16x16x32_bf16 v[120:123], v[160:163], v[200:203], 0
	v_mfma_f32_16x16x32_bf16 v[112:115], v[152:155], v[208:211], 0
	v_mfma_f32_16x16x32_bf16 v[104:107], v[160:163], v[208:211], 0
	v_mfma_f32_16x16x32_bf16 v[96:99], v[152:155], v[216:219], 0
	v_mfma_f32_16x16x32_bf16 v[88:91], v[160:163], v[216:219], 0
	v_mfma_f32_16x16x32_bf16 v[80:83], v[152:155], v[224:227], 0
	v_mfma_f32_16x16x32_bf16 v[72:75], v[160:163], v[224:227], 0
	v_mfma_f32_16x16x32_bf16 v[128:131], v[156:159], v[204:207], v[128:131]
	v_mfma_f32_16x16x32_bf16 v[120:123], v[168:171], v[204:207], v[120:123]
	v_mfma_f32_16x16x32_bf16 v[112:115], v[156:159], v[212:215], v[112:115]
	v_mfma_f32_16x16x32_bf16 v[104:107], v[168:171], v[212:215], v[104:107]
	v_mfma_f32_16x16x32_bf16 v[96:99], v[156:159], v[220:223], v[96:99]
	v_mfma_f32_16x16x32_bf16 v[88:91], v[168:171], v[220:223], v[88:91]
	v_mfma_f32_16x16x32_bf16 v[80:83], v[156:159], v[228:231], v[80:83]
	v_mfma_f32_16x16x32_bf16 v[72:75], v[168:171], v[228:231], v[72:75]
	v_mfma_f32_16x16x32_bf16 v[124:127], v[174:177], v[200:203], 0
	v_mfma_f32_16x16x32_bf16 v[116:119], v[182:185], v[200:203], 0
	v_mfma_f32_16x16x32_bf16 v[108:111], v[174:177], v[208:211], 0
	v_mfma_f32_16x16x32_bf16 v[100:103], v[182:185], v[208:211], 0
	v_mfma_f32_16x16x32_bf16 v[92:95], v[174:177], v[216:219], 0
	v_mfma_f32_16x16x32_bf16 v[84:87], v[182:185], v[216:219], 0
	v_mfma_f32_16x16x32_bf16 v[76:79], v[174:177], v[224:227], 0
	v_mfma_f32_16x16x32_bf16 v[68:71], v[182:185], v[224:227], 0
	v_mfma_f32_16x16x32_bf16 v[124:127], v[178:181], v[204:207], v[124:127]
	v_mfma_f32_16x16x32_bf16 v[116:119], v[186:189], v[204:207], v[116:119]
	v_mfma_f32_16x16x32_bf16 v[108:111], v[178:181], v[212:215], v[108:111]
	v_mfma_f32_16x16x32_bf16 v[100:103], v[186:189], v[212:215], v[100:103]
	v_mfma_f32_16x16x32_bf16 v[92:95], v[178:181], v[220:223], v[92:95]
	v_mfma_f32_16x16x32_bf16 v[84:87], v[186:189], v[220:223], v[84:87]
	v_mfma_f32_16x16x32_bf16 v[76:79], v[178:181], v[228:231], v[76:79]
	v_mfma_f32_16x16x32_bf16 v[68:71], v[186:189], v[228:231], v[68:71]
	s_barrier
	s_add_i32 s33, s82, s20
	v_lshl_add_u64 v[146:147], s[70:71], 0, v[134:135]
	s_mov_b32 m0, s33
	ds_read_b128 v[200:203], v151 offset:16384
	ds_read_b128 v[204:207], v151 offset:17408
	ds_read_b128 v[208:211], v151 offset:18432
	ds_read_b128 v[212:215], v151 offset:19456
	ds_read_b128 v[216:219], v151 offset:20480
	ds_read_b128 v[220:223], v151 offset:21504
	ds_read_b128 v[224:227], v151 offset:22528
	ds_read_b128 v[228:231], v151 offset:23552
	global_load_lds_dwordx4 v[146:147], off
	s_add_i32 m0, s33, 0x2000
	s_add_u32 s82, s70, 0x40000
	v_lshl_add_u64 v[164:165], s[70:71], 0, v[138:139]
	s_addc_u32 s83, s71, 0
	s_add_i32 s6, s6, s20
	global_load_lds_dwordx4 v[164:165], off
	v_lshl_add_u64 v[232:233], s[82:83], 0, v[134:135]
	s_mov_b32 m0, s6
	v_lshl_add_u64 v[234:235], s[72:73], 0, v[136:137]
	global_load_lds_dwordx4 v[232:233], off
	v_lshl_add_u64 v[232:233], s[82:83], 0, v[138:139]
	s_add_i32 m0, s6, 0x2000
	s_nop 0
	global_load_lds_dwordx4 v[232:233], off
	v_lshl_add_u64 v[232:233], s[72:73], 0, v[132:133]
	s_mov_b32 m0, s35
	s_nop 0
	global_load_lds_dwordx4 v[232:233], off
	s_mov_b32 m0, s54
	s_nop 0
	global_load_lds_dwordx4 v[234:235], off
	s_waitcnt vmcnt(8)
	s_waitcnt lgkmcnt(0)
	s_barrier
	s_waitcnt lgkmcnt(0)
	v_mfma_f32_16x16x32_bf16 v[64:67], v[152:155], v[200:203], 0
	v_mfma_f32_16x16x32_bf16 v[56:59], v[160:163], v[200:203], 0
	v_mfma_f32_16x16x32_bf16 v[48:51], v[152:155], v[208:211], 0
	v_mfma_f32_16x16x32_bf16 v[40:43], v[160:163], v[208:211], 0
	v_mfma_f32_16x16x32_bf16 v[32:35], v[152:155], v[216:219], 0
	v_mfma_f32_16x16x32_bf16 v[24:27], v[160:163], v[216:219], 0
	v_mfma_f32_16x16x32_bf16 v[16:19], v[152:155], v[224:227], 0
	v_mfma_f32_16x16x32_bf16 v[8:11], v[160:163], v[224:227], 0
	v_mfma_f32_16x16x32_bf16 v[64:67], v[156:159], v[204:207], v[64:67]
	v_mfma_f32_16x16x32_bf16 v[56:59], v[168:171], v[204:207], v[56:59]
	v_mfma_f32_16x16x32_bf16 v[48:51], v[156:159], v[212:215], v[48:51]
	v_mfma_f32_16x16x32_bf16 v[40:43], v[168:171], v[212:215], v[40:43]
	v_mfma_f32_16x16x32_bf16 v[32:35], v[156:159], v[220:223], v[32:35]
	v_mfma_f32_16x16x32_bf16 v[24:27], v[168:171], v[220:223], v[24:27]
	v_mfma_f32_16x16x32_bf16 v[16:19], v[156:159], v[228:231], v[16:19]
	v_mfma_f32_16x16x32_bf16 v[8:11], v[168:171], v[228:231], v[8:11]
	v_mfma_f32_16x16x32_bf16 v[60:63], v[174:177], v[200:203], 0
	v_mfma_f32_16x16x32_bf16 v[52:55], v[182:185], v[200:203], 0
	v_mfma_f32_16x16x32_bf16 v[44:47], v[174:177], v[208:211], 0
	v_mfma_f32_16x16x32_bf16 v[36:39], v[182:185], v[208:211], 0
	v_mfma_f32_16x16x32_bf16 v[28:31], v[174:177], v[216:219], 0
	v_mfma_f32_16x16x32_bf16 v[20:23], v[182:185], v[216:219], 0
	v_mfma_f32_16x16x32_bf16 v[12:15], v[174:177], v[224:227], 0
	v_mfma_f32_16x16x32_bf16 v[4:7], v[182:185], v[224:227], 0
	v_mfma_f32_16x16x32_bf16 v[60:63], v[178:181], v[204:207], v[60:63]
	v_mfma_f32_16x16x32_bf16 v[52:55], v[186:189], v[204:207], v[52:55]
	v_mfma_f32_16x16x32_bf16 v[44:47], v[178:181], v[212:215], v[44:47]
	v_mfma_f32_16x16x32_bf16 v[36:39], v[186:189], v[212:215], v[36:39]
	v_mfma_f32_16x16x32_bf16 v[28:31], v[178:181], v[220:223], v[28:31]
	v_mfma_f32_16x16x32_bf16 v[20:23], v[186:189], v[220:223], v[20:23]
	v_mfma_f32_16x16x32_bf16 v[12:15], v[178:181], v[228:231], v[12:15]
	v_mfma_f32_16x16x32_bf16 v[4:7], v[186:189], v[228:231], v[4:7]
	s_barrier
	s_add_i32 s6, 0, 0x18000
	v_add_u32_e32 v2, s6, v148
	s_add_i32 s33, 0, 0x1c000
	ds_read_b128 v[152:155], v2
	ds_read_b128 v[156:159], v2 offset:1024
	ds_read_b128 v[160:163], v2 offset:2048
	ds_read_b128 v[168:171], v2 offset:3072
	v_add_u32_e32 v2, s33, v148
	ds_read_b128 v[174:177], v2
	ds_read_b128 v[178:181], v2 offset:1024
	ds_read_b128 v[182:185], v2 offset:2048
	ds_read_b128 v[186:189], v2 offset:3072
	s_add_u32 s72, s72, 0x40000
	s_addc_u32 s73, s73, 0
	s_mov_b32 m0, s55
	v_lshl_add_u64 v[236:237], s[72:73], 0, v[132:133]
	ds_read_b128 v[200:203], v151 offset:32768
	ds_read_b128 v[204:207], v151 offset:33792
	ds_read_b128 v[208:211], v151 offset:34816
	ds_read_b128 v[212:215], v151 offset:35840
	ds_read_b128 v[216:219], v151 offset:36864
	ds_read_b128 v[220:223], v151 offset:37888
	ds_read_b128 v[224:227], v151 offset:38912
	ds_read_b128 v[228:231], v151 offset:39936
	global_load_lds_dwordx4 v[236:237], off
	v_lshl_add_u64 v[236:237], s[72:73], 0, v[136:137]
	s_mov_b32 m0, s56
	s_nop 0
	global_load_lds_dwordx4 v[236:237], off
	s_waitcnt vmcnt(8)
	s_waitcnt lgkmcnt(0)
	s_barrier
	s_waitcnt lgkmcnt(0)
	v_mfma_f32_16x16x32_bf16 v[128:131], v[152:155], v[200:203], v[128:131]
	v_mfma_f32_16x16x32_bf16 v[120:123], v[160:163], v[200:203], v[120:123]
	v_mfma_f32_16x16x32_bf16 v[112:115], v[152:155], v[208:211], v[112:115]
	v_mfma_f32_16x16x32_bf16 v[104:107], v[160:163], v[208:211], v[104:107]
	v_mfma_f32_16x16x32_bf16 v[96:99], v[152:155], v[216:219], v[96:99]
	v_mfma_f32_16x16x32_bf16 v[88:91], v[160:163], v[216:219], v[88:91]
	v_mfma_f32_16x16x32_bf16 v[80:83], v[152:155], v[224:227], v[80:83]
	v_mfma_f32_16x16x32_bf16 v[72:75], v[160:163], v[224:227], v[72:75]
	v_mfma_f32_16x16x32_bf16 v[128:131], v[156:159], v[204:207], v[128:131]
	v_mfma_f32_16x16x32_bf16 v[120:123], v[168:171], v[204:207], v[120:123]
	v_mfma_f32_16x16x32_bf16 v[112:115], v[156:159], v[212:215], v[112:115]
	v_mfma_f32_16x16x32_bf16 v[104:107], v[168:171], v[212:215], v[104:107]
	v_mfma_f32_16x16x32_bf16 v[96:99], v[156:159], v[220:223], v[96:99]
	v_mfma_f32_16x16x32_bf16 v[88:91], v[168:171], v[220:223], v[88:91]
	v_mfma_f32_16x16x32_bf16 v[80:83], v[156:159], v[228:231], v[80:83]
	v_mfma_f32_16x16x32_bf16 v[72:75], v[168:171], v[228:231], v[72:75]
	v_mfma_f32_16x16x32_bf16 v[124:127], v[174:177], v[200:203], v[124:127]
	v_mfma_f32_16x16x32_bf16 v[116:119], v[182:185], v[200:203], v[116:119]
	v_mfma_f32_16x16x32_bf16 v[108:111], v[174:177], v[208:211], v[108:111]
	v_mfma_f32_16x16x32_bf16 v[100:103], v[182:185], v[208:211], v[100:103]
	v_mfma_f32_16x16x32_bf16 v[92:95], v[174:177], v[216:219], v[92:95]
	v_mfma_f32_16x16x32_bf16 v[84:87], v[182:185], v[216:219], v[84:87]
	v_mfma_f32_16x16x32_bf16 v[76:79], v[174:177], v[224:227], v[76:79]
	v_mfma_f32_16x16x32_bf16 v[68:71], v[182:185], v[224:227], v[68:71]
	v_mfma_f32_16x16x32_bf16 v[124:127], v[178:181], v[204:207], v[124:127]
	v_mfma_f32_16x16x32_bf16 v[116:119], v[186:189], v[204:207], v[116:119]
	v_mfma_f32_16x16x32_bf16 v[108:111], v[178:181], v[212:215], v[108:111]
	v_mfma_f32_16x16x32_bf16 v[100:103], v[186:189], v[212:215], v[100:103]
	v_mfma_f32_16x16x32_bf16 v[92:95], v[178:181], v[220:223], v[92:95]
	v_mfma_f32_16x16x32_bf16 v[84:87], v[186:189], v[220:223], v[84:87]
	v_mfma_f32_16x16x32_bf16 v[76:79], v[178:181], v[228:231], v[76:79]
	v_mfma_f32_16x16x32_bf16 v[68:71], v[186:189], v[228:231], v[68:71]
	s_barrier
	s_add_i32 s6, s6, s20
	v_lshl_add_u64 v[146:147], v[146:147], 0, s[30:31]
	s_mov_b32 m0, s6
	ds_read_b128 v[200:203], v151 offset:49152
	ds_read_b128 v[204:207], v151 offset:50176
	ds_read_b128 v[208:211], v151 offset:51200
	ds_read_b128 v[212:215], v151 offset:52224
	ds_read_b128 v[216:219], v151 offset:53248
	ds_read_b128 v[220:223], v151 offset:54272
	ds_read_b128 v[224:227], v151 offset:55296
	ds_read_b128 v[228:231], v151 offset:56320
	global_load_lds_dwordx4 v[146:147], off
	s_add_i32 m0, s6, 0x2000
	s_add_u32 s70, s70, 0x40080
	v_lshl_add_u64 v[146:147], v[164:165], 0, s[30:31]
	s_addc_u32 s71, s71, 0
	s_add_i32 s6, s33, s20
	global_load_lds_dwordx4 v[146:147], off
	v_lshl_add_u64 v[146:147], s[70:71], 0, v[134:135]
	s_mov_b32 m0, s6
	s_nop 0
	global_load_lds_dwordx4 v[146:147], off
	v_lshl_add_u64 v[146:147], s[70:71], 0, v[138:139]
	s_add_i32 m0, s6, 0x2000
	s_nop 0
	global_load_lds_dwordx4 v[146:147], off
	v_lshl_add_u64 v[146:147], v[232:233], 0, s[30:31]
	s_mov_b32 m0, s76
	s_nop 0
	global_load_lds_dwordx4 v[146:147], off
	v_lshl_add_u64 v[146:147], v[234:235], 0, s[30:31]
	s_mov_b32 m0, s77
	s_nop 0
	global_load_lds_dwordx4 v[146:147], off
	s_waitcnt vmcnt(8)
	s_waitcnt lgkmcnt(0)
	s_barrier
	s_waitcnt lgkmcnt(0)
	v_mfma_f32_16x16x32_bf16 v[64:67], v[152:155], v[200:203], v[64:67]
	v_mfma_f32_16x16x32_bf16 v[56:59], v[160:163], v[200:203], v[56:59]
	v_mfma_f32_16x16x32_bf16 v[48:51], v[152:155], v[208:211], v[48:51]
	v_mfma_f32_16x16x32_bf16 v[40:43], v[160:163], v[208:211], v[40:43]
	v_mfma_f32_16x16x32_bf16 v[32:35], v[152:155], v[216:219], v[32:35]
	v_mfma_f32_16x16x32_bf16 v[24:27], v[160:163], v[216:219], v[24:27]
	v_mfma_f32_16x16x32_bf16 v[16:19], v[152:155], v[224:227], v[16:19]
	v_mfma_f32_16x16x32_bf16 v[8:11], v[160:163], v[224:227], v[8:11]
	v_mfma_f32_16x16x32_bf16 v[64:67], v[156:159], v[204:207], v[64:67]
	v_mfma_f32_16x16x32_bf16 v[56:59], v[168:171], v[204:207], v[56:59]
	v_mfma_f32_16x16x32_bf16 v[48:51], v[156:159], v[212:215], v[48:51]
	v_mfma_f32_16x16x32_bf16 v[40:43], v[168:171], v[212:215], v[40:43]
	v_mfma_f32_16x16x32_bf16 v[32:35], v[156:159], v[220:223], v[32:35]
	v_mfma_f32_16x16x32_bf16 v[24:27], v[168:171], v[220:223], v[24:27]
	v_mfma_f32_16x16x32_bf16 v[16:19], v[156:159], v[228:231], v[16:19]
	v_mfma_f32_16x16x32_bf16 v[8:11], v[168:171], v[228:231], v[8:11]
	v_mfma_f32_16x16x32_bf16 v[60:63], v[174:177], v[200:203], v[60:63]
	v_mfma_f32_16x16x32_bf16 v[52:55], v[182:185], v[200:203], v[52:55]
	v_mfma_f32_16x16x32_bf16 v[44:47], v[174:177], v[208:211], v[44:47]
	v_mfma_f32_16x16x32_bf16 v[36:39], v[182:185], v[208:211], v[36:39]
	v_mfma_f32_16x16x32_bf16 v[28:31], v[174:177], v[216:219], v[28:31]
	v_mfma_f32_16x16x32_bf16 v[20:23], v[182:185], v[216:219], v[20:23]
	v_mfma_f32_16x16x32_bf16 v[12:15], v[174:177], v[224:227], v[12:15]
	v_mfma_f32_16x16x32_bf16 v[4:7], v[182:185], v[224:227], v[4:7]
	v_mfma_f32_16x16x32_bf16 v[60:63], v[178:181], v[204:207], v[60:63]
	v_mfma_f32_16x16x32_bf16 v[52:55], v[186:189], v[204:207], v[52:55]
	v_mfma_f32_16x16x32_bf16 v[44:47], v[178:181], v[212:215], v[44:47]
	v_mfma_f32_16x16x32_bf16 v[36:39], v[186:189], v[212:215], v[36:39]
	v_mfma_f32_16x16x32_bf16 v[28:31], v[178:181], v[220:223], v[28:31]
	v_mfma_f32_16x16x32_bf16 v[20:23], v[186:189], v[220:223], v[20:23]
	v_mfma_f32_16x16x32_bf16 v[12:15], v[178:181], v[228:231], v[12:15]
	v_mfma_f32_16x16x32_bf16 v[4:7], v[186:189], v[228:231], v[4:7]
	s_barrier
	s_add_i32 s80, s80, 2
	s_add_u32 s68, s68, 0x100
	s_addc_u32 s69, s69, 0
	s_add_u32 s61, s61, 0x100
	s_addc_u32 s67, s67, 0
